# MFMA-to-VALU padding after QK trimmed from 13 to 11+1 wait states (s_nop 3 -> s_nop 1)
# speedup vs baseline: 1.0012x; 1.0012x over previous
; template <bool WIN>
; __device__ __forceinline__ void partialSM(f32x16& p0, f32x16& p1, float& m_reg, float& mn, float& alpha) {
;   constexpr float C = SCALE * 1.4426950408889634f;
;   float pmax = p0[0];
; #pragma unroll
;   for (int r = 1; r < 16; ++r) pmax = fmaxf(pmax, p0[r]);
; #pragma unroll
;   for (int r = 0; r < 16; ++r) pmax = fmaxf(pmax, p1[r]);
;   { auto rr = __builtin_amdgcn_permlane32_swap(__float_as_uint(pmax), __float_as_uint(pmax), false, false);
;     pmax = fmaxf(__uint_as_float(rr[0]), __uint_as_float(rr[1])); }
;   if (__builtin_expect(__all(pmax - m_reg <= THR / SCALE), 1)) { mn = m_reg; alpha = 1.f; }
;   else { mn = fmaxf(m_reg, pmax); alpha = __builtin_amdgcn_exp2f((m_reg - mn) * C); m_reg = mn; }
;   float mnC = -mn * C;
; #pragma unroll
;   for (int r = 0; r < 16; ++r) p0[r] = fmaf(p0[r], C, mnC);
; #pragma unroll
;   for (int r = 0; r < 16; ++r) p1[r] = fmaf(p1[r], C, mnC);
; #pragma unroll
;   for (int r = 0; r < 16; ++r) p0[r] = __builtin_amdgcn_exp2f(p0[r]);
; }
; __device__ __forceinline__ void finishSM(f32x16& p0, f32x16& p1, float alpha, float& l_reg, bf16x8& pa0, bf16x8& pa1, bf16x8& pa2, bf16x8& pa3) {
; #pragma unroll
;   for (int r = 0; r < 16; ++r) p1[r] = __builtin_amdgcn_exp2f(p1[r]);
;   float ps = 0;
; #pragma unroll
;   for (int r = 0; r < 16; ++r) ps += p0[r];
; #pragma unroll
;   for (int r = 0; r < 16; ++r) ps += p1[r];
;   { auto rr = __builtin_amdgcn_permlane32_swap(__float_as_uint(ps), __float_as_uint(ps), false, false);
;     ps = __uint_as_float(rr[0]) + __uint_as_float(rr[1]); }
;   l_reg = l_reg * alpha + ps;
;     ...
;   PK4(p0, 0, pa0); PK4(p0, 8, pa1); PK4(p1, 0, pa2); PK4(p1, 8, pa3);
;     ...
; }
; template <bool WIN>
; __device__ __forceinline__ void qkt(f32x16& p0, f32x16& p1, const bf16_t* Ks, const bf16x8* qr, int r32, int hi, int dq) {
;   p0 = f32x16{}; p1 = f32x16{};
;   if (WIN) {
;     const int t = 4 * hi - dq + 128;
; #pragma unroll
;     for (int r = 0; r < 16; ++r) { const unsigned d0 = (unsigned)(t + (r & 3) + 8 * (r >> 2)), d1 = d0 + 32u;
;       p0[r] = d0 > 256u ? -1e30f : 0.f; p1[r] = d1 > 256u ? -1e30f : 0.f; }
;   }
; #pragma unroll
;   for (int d0 = 0; d0 < 8; ++d0) { int cb = (d0 * 16 + hi * 8) * 2;
;     bf16x8 b0 = *reinterpret_cast<const bf16x8*>((const char*)Ks + KSWZ(r32, cb));
;     bf16x8 b1 = *reinterpret_cast<const bf16x8*>((const char*)Ks + KSWZ(32 + r32, cb));
.LBB0_643:
	s_and_b32 s69, s68, 1
	s_xor_b32 s33, s69, 1
	s_lshl_b32 s0, s33, 14
	s_add_i32 s0, s35, s0
	v_lshl_add_u64 v[254:255], s[22:23], 0, v[206:207]
	s_mov_b32 m0, s0
	s_nop 0
	global_load_lds_dwordx4 v[254:255], off
	v_lshl_add_u64 v[254:255], s[22:23], 0, v[204:205]
	s_add_i32 m0, s0, 0x400
	s_nop 0
	global_load_lds_dwordx4 v[254:255], off
	s_setprio 1
	s_lshl_b32 s0, s69, 14
	v_add3_u32 v0, s0, v209, v199
	ds_read_b128 v[130:133], v0
	ds_read_b128 v[134:137], v0 offset:8192
	v_add3_u32 v0, s0, v210, v199
	ds_read_b128 v[232:235], v0
	ds_read_b128 v[236:239], v0 offset:8192
	v_add3_u32 v0, s0, v211, v199
	ds_read_b128 v[246:249], v0
	ds_read_b128 v[250:253], v0 offset:8192
	s_waitcnt lgkmcnt(4)
	v_mfma_f32_32x32x16_bf16 v[146:161], v[130:133], v[162:165], 0
	v_mfma_f32_32x32x16_bf16 v[130:145], v[134:137], v[162:165], 0
	s_waitcnt lgkmcnt(2)
	v_mfma_f32_32x32x16_bf16 v[146:161], v[232:235], v[166:169], v[146:161]
	v_mfma_f32_32x32x16_bf16 v[130:145], v[236:239], v[166:169], v[130:145]
	v_add3_u32 v0, s0, v212, v199
	ds_read_b128 v[232:235], v0
	ds_read_b128 v[236:239], v0 offset:8192
	s_waitcnt lgkmcnt(2)
	v_mfma_f32_32x32x16_bf16 v[146:161], v[246:249], v[170:173], v[146:161]
	v_mfma_f32_32x32x16_bf16 v[130:145], v[250:253], v[170:173], v[130:145]
	v_add3_u32 v0, s0, v213, v199
	ds_read_b128 v[246:249], v0
	ds_read_b128 v[250:253], v0 offset:8192
	s_waitcnt lgkmcnt(2)
	v_mfma_f32_32x32x16_bf16 v[146:161], v[232:235], v[174:177], v[146:161]
	v_mfma_f32_32x32x16_bf16 v[130:145], v[236:239], v[174:177], v[130:145]
	v_add3_u32 v0, s0, v214, v199
	ds_read_b128 v[232:235], v0
	ds_read_b128 v[236:239], v0 offset:8192
	s_waitcnt lgkmcnt(2)
	v_mfma_f32_32x32x16_bf16 v[146:161], v[246:249], v[178:181], v[146:161]
	v_mfma_f32_32x32x16_bf16 v[130:145], v[250:253], v[178:181], v[130:145]
	v_add3_u32 v0, s0, v215, v199
	ds_read_b128 v[246:249], v0
	ds_read_b128 v[250:253], v0 offset:8192
	s_waitcnt lgkmcnt(2)
	v_mfma_f32_32x32x16_bf16 v[146:161], v[232:235], v[182:185], v[146:161]
	v_mfma_f32_32x32x16_bf16 v[130:145], v[236:239], v[182:185], v[130:145]
	v_add3_u32 v0, s0, v216, v199
	ds_read_b128 v[232:235], v0
	ds_read_b128 v[236:239], v0 offset:8192
	s_waitcnt lgkmcnt(2)
	v_mfma_f32_32x32x16_bf16 v[146:161], v[246:249], v[186:189], v[146:161]
	v_mfma_f32_32x32x16_bf16 v[130:145], v[250:253], v[186:189], v[130:145]
	s_waitcnt lgkmcnt(0)
	v_mfma_f32_32x32x16_bf16 v[146:161], v[232:235], v[190:193], v[146:161]
	v_mfma_f32_32x32x16_bf16 v[130:145], v[236:239], v[190:193], v[130:145]
	s_setprio 0
	s_nop 7
	s_nop 1
	v_max3_f32 v0, v146, v147, v148
	v_max3_f32 v231, v130, v131, v132
	v_max3_f32 v0, v0, v149, v150
	v_max3_f32 v231, v231, v133, v134
	v_max3_f32 v0, v0, v151, v152
	v_max3_f32 v231, v231, v135, v136
	v_max3_f32 v0, v0, v153, v154
	v_max3_f32 v231, v231, v137, v138
	v_max3_f32 v0, v0, v155, v156
	v_max3_f32 v231, v231, v139, v140
	v_max3_f32 v0, v0, v157, v158
	v_max3_f32 v231, v231, v141, v142
	v_max3_f32 v0, v0, v159, v160
	v_max3_f32 v231, v231, v143, v144
	v_max3_f32 v0, v0, v161, v231
	v_max_f32_e32 v0, v0, v145
	v_mov_b32_e32 v231, v0
	s_nop 1
	v_permlane32_swap_b32_e32 v0, v231
	v_max_f32_e32 v0, v0, v231
	v_sub_f32_e32 v231, v0, v229
	s_mov_b32 s0, 0x42b504f3
	v_cmp_ge_f32_e32 vcc, s0, v231
	v_max_f32_e32 v232, v229, v0
	s_cmp_eq_u64 vcc, exec
	s_cselect_b64 vcc, -1, 0
	v_sub_f32_e32 v0, v229, v232
	v_cndmask_b32_e32 v229, v232, v229, vcc
	v_mul_f32_e32 v231, 0xbe0293ee, v229
	v_fmamk_f32 v146, v146, 0x3e0293ee, v231
	v_fmamk_f32 v147, v147, 0x3e0293ee, v231
	v_fmamk_f32 v148, v148, 0x3e0293ee, v231
	v_fmamk_f32 v149, v149, 0x3e0293ee, v231
	v_fmamk_f32 v150, v150, 0x3e0293ee, v231
	v_fmamk_f32 v151, v151, 0x3e0293ee, v231
	v_fmamk_f32 v152, v152, 0x3e0293ee, v231
	v_fmamk_f32 v153, v153, 0x3e0293ee, v231
	v_fmamk_f32 v154, v154, 0x3e0293ee, v231
	v_fmamk_f32 v155, v155, 0x3e0293ee, v231
	v_fmamk_f32 v156, v156, 0x3e0293ee, v231
	v_fmamk_f32 v157, v157, 0x3e0293ee, v231
	v_fmamk_f32 v158, v158, 0x3e0293ee, v231
	v_fmamk_f32 v159, v159, 0x3e0293ee, v231
	v_fmamk_f32 v160, v160, 0x3e0293ee, v231
	v_fmamk_f32 v161, v161, 0x3e0293ee, v231
	v_fmamk_f32 v130, v130, 0x3e0293ee, v231
	v_fmamk_f32 v131, v131, 0x3e0293ee, v231
	v_fmamk_f32 v132, v132, 0x3e0293ee, v231
	v_fmamk_f32 v133, v133, 0x3e0293ee, v231
	v_fmamk_f32 v134, v134, 0x3e0293ee, v231
	v_fmamk_f32 v135, v135, 0x3e0293ee, v231
	v_fmamk_f32 v136, v136, 0x3e0293ee, v231
	v_fmamk_f32 v137, v137, 0x3e0293ee, v231
	v_fmamk_f32 v138, v138, 0x3e0293ee, v231
	v_fmamk_f32 v139, v139, 0x3e0293ee, v231
	v_fmamk_f32 v140, v140, 0x3e0293ee, v231
	v_fmamk_f32 v141, v141, 0x3e0293ee, v231
	v_fmamk_f32 v142, v142, 0x3e0293ee, v231
	v_fmamk_f32 v143, v143, 0x3e0293ee, v231
	v_fmamk_f32 v144, v144, 0x3e0293ee, v231
	v_fmac_f32_e32 v231, 0x3e0293ee, v145
	v_exp_f32_e32 v145, v146
	v_exp_f32_e32 v146, v147
	v_exp_f32_e32 v147, v148
	v_exp_f32_e32 v148, v149
	v_exp_f32_e32 v149, v150
	v_exp_f32_e32 v150, v151
	v_exp_f32_e32 v151, v152
	v_exp_f32_e32 v152, v153
	v_exp_f32_e32 v153, v154
	v_exp_f32_e32 v154, v155
	v_exp_f32_e32 v155, v156
	v_exp_f32_e32 v156, v157
	v_exp_f32_e32 v157, v158
	v_exp_f32_e32 v158, v159
	v_exp_f32_e32 v159, v160
	v_exp_f32_e32 v160, v161
	v_exp_f32_e32 v161, v134
	v_add_f32_e32 v134, v146, v145
	v_add_f32_e32 v134, v147, v134
	v_add_f32_e32 v134, v148, v134
	v_add_f32_e32 v134, v149, v134
	v_add_f32_e32 v134, v150, v134
	v_add_f32_e32 v134, v151, v134
	v_add_f32_e32 v134, v152, v134
	v_add_f32_e32 v134, v153, v134
; __device__ __forceinline__ void finishSM(f32x16& p0, f32x16& p1, float alpha, float& l_reg, bf16x8& pa0, bf16x8& pa1, bf16x8& pa2, bf16x8& pa3) {
; #pragma unroll
;   for (int r = 0; r < 16; ++r) p1[r] = __builtin_amdgcn_exp2f(p1[r]);
;   float ps = 0;
; #pragma unroll
;   for (int r = 0; r < 16; ++r) ps += p0[r];
; #pragma unroll
;   for (int r = 0; r < 16; ++r) ps += p1[r];
;   { auto rr = __builtin_amdgcn_permlane32_swap(__float_as_uint(ps), __float_as_uint(ps), false, false);
;     ps = __uint_as_float(rr[0]) + __uint_as_float(rr[1]); }
;   l_reg = l_reg * alpha + ps;
;     ...
;   PK4(p0, 0, pa0); PK4(p0, 8, pa1); PK4(p1, 0, pa2); PK4(p1, 8, pa3);
;     ...
; }
	v_add_f32_e32 v134, v154, v134
	v_add_f32_e32 v134, v155, v134
	v_add_f32_e32 v134, v156, v134
	v_exp_f32_e32 v130, v130
	v_add_f32_e32 v134, v157, v134
	v_exp_f32_e32 v131, v131
	v_add_f32_e32 v134, v158, v134
	v_exp_f32_e32 v132, v132
	v_add_f32_e32 v134, v159, v134
	v_exp_f32_e32 v133, v133
	v_add_f32_e32 v134, v160, v134
	v_add_f32_e32 v134, v130, v134
	v_exp_f32_e32 v233, v135
	v_add_f32_e32 v134, v131, v134
	v_exp_f32_e32 v234, v136
	v_add_f32_e32 v134, v132, v134
	v_exp_f32_e32 v235, v137
	v_add_f32_e32 v134, v133, v134
	v_exp_f32_e32 v138, v138
	v_add_f32_e32 v134, v161, v134
	v_exp_f32_e32 v139, v139
	v_add_f32_e32 v134, v233, v134
	v_exp_f32_e32 v140, v140
	v_add_f32_e32 v134, v234, v134
	v_exp_f32_e32 v141, v141
	v_add_f32_e32 v134, v235, v134
	v_exp_f32_e32 v236, v142
	v_add_f32_e32 v134, v138, v134
	v_exp_f32_e32 v237, v143
	v_add_f32_e32 v134, v139, v134
	v_exp_f32_e32 v238, v144
	v_add_f32_e32 v134, v140, v134
	v_mul_f32_e32 v0, 0x3e0293ee, v0
	v_exp_f32_e32 v239, v231
	v_add_f32_e32 v134, v141, v134
	v_exp_f32_e32 v0, v0
	v_add_f32_e32 v134, v236, v134
	v_add_f32_e32 v134, v237, v134
	v_add_f32_e32 v134, v238, v134
	v_add_f32_e32 v231, v239, v134
	v_cndmask_b32_e64 v0, v0, 1.0, vcc
	v_mov_b32_e32 v232, v231
	v_cvt_pk_bf16_f32 v134, v145, v146
	v_cvt_pk_bf16_f32 v135, v147, v148
	v_cvt_pk_bf16_f32 v136, v149, v150
	v_cvt_pk_bf16_f32 v137, v151, v152
	v_cvt_pk_bf16_f32 v142, v153, v154
	v_cvt_pk_bf16_f32 v143, v155, v156
	v_cvt_pk_bf16_f32 v144, v157, v158
	v_cvt_pk_bf16_f32 v145, v159, v160
	v_cvt_pk_bf16_f32 v130, v130, v131
	v_cvt_pk_bf16_f32 v131, v132, v133
	v_cvt_pk_bf16_f32 v132, v161, v233
	v_cvt_pk_bf16_f32 v133, v234, v235
	v_cvt_pk_bf16_f32 v138, v138, v139
	v_cvt_pk_bf16_f32 v139, v140, v141
	v_cvt_pk_bf16_f32 v140, v236, v237
	v_cvt_pk_bf16_f32 v141, v238, v239
	v_permlane32_swap_b32_e32 v231, v232
	v_permlane32_swap_b32_e32 v134, v136
	v_permlane32_swap_b32_e32 v135, v137
	v_permlane32_swap_b32_e32 v142, v144
	v_permlane32_swap_b32_e32 v143, v145
	v_permlane32_swap_b32_e32 v130, v132
	v_permlane32_swap_b32_e32 v131, v133
	v_permlane32_swap_b32_e32 v138, v140
	v_permlane32_swap_b32_e32 v139, v141
	v_cmp_gt_f32_e32 vcc, 1.0, v0
	s_cbranch_vccz .LBB0_649
	s_and_saveexec_b64 s[0:1], s[6:7]
	ds_write_b32 v228, v0 offset:128
	s_or_b64 exec, exec, s[0:1]
	s_waitcnt lgkmcnt(0)
	v_add_u32_e32 v146, s67, v223
	ds_read_b128 v[158:161], v146 offset:224
	ds_read_b128 v[154:157], v146 offset:192
	ds_read_b128 v[150:153], v146 offset:160
	ds_read_b128 v[146:149], v146 offset:128
	s_waitcnt lgkmcnt(0)
	v_pk_mul_f32 v[126:127], v[126:127], v[158:159]
	v_pk_mul_f32 v[122:123], v[122:123], v[154:155]
	v_pk_mul_f32 v[118:119], v[118:119], v[150:151]
	v_pk_mul_f32 v[128:129], v[128:129], v[160:161]
	v_pk_mul_f32 v[124:125], v[124:125], v[156:157]
	v_pk_mul_f32 v[120:121], v[120:121], v[152:153]
	v_pk_mul_f32 v[116:117], v[116:117], v[148:149]
	v_pk_mul_f32 v[114:115], v[114:115], v[146:147]
	v_pk_mul_f32 v[110:111], v[110:111], v[158:159]
	v_pk_mul_f32 v[106:107], v[106:107], v[154:155]
	v_pk_mul_f32 v[102:103], v[102:103], v[150:151]
	v_pk_mul_f32 v[112:113], v[112:113], v[160:161]
	v_pk_mul_f32 v[108:109], v[108:109], v[156:157]
	v_pk_mul_f32 v[104:105], v[104:105], v[152:153]
	v_pk_mul_f32 v[100:101], v[100:101], v[148:149]
	v_pk_mul_f32 v[98:99], v[98:99], v[146:147]
	v_pk_mul_f32 v[94:95], v[94:95], v[158:159]
	v_pk_mul_f32 v[90:91], v[90:91], v[154:155]
	v_pk_mul_f32 v[86:87], v[86:87], v[150:151]
	v_pk_mul_f32 v[96:97], v[96:97], v[160:161]
	v_pk_mul_f32 v[92:93], v[92:93], v[156:157]
	v_pk_mul_f32 v[88:89], v[88:89], v[152:153]
	v_pk_mul_f32 v[84:85], v[84:85], v[148:149]
	v_pk_mul_f32 v[82:83], v[82:83], v[146:147]
	v_pk_mul_f32 v[78:79], v[78:79], v[158:159]
	v_pk_mul_f32 v[74:75], v[74:75], v[154:155]
	v_pk_mul_f32 v[70:71], v[70:71], v[150:151]
	v_pk_mul_f32 v[80:81], v[80:81], v[160:161]
	v_pk_mul_f32 v[76:77], v[76:77], v[156:157]
	v_pk_mul_f32 v[72:73], v[72:73], v[152:153]
	v_pk_mul_f32 v[68:69], v[68:69], v[148:149]
	v_pk_mul_f32 v[66:67], v[66:67], v[146:147]
	v_pk_mul_f32 v[62:63], v[62:63], v[158:159]
	v_pk_mul_f32 v[58:59], v[58:59], v[154:155]
	v_pk_mul_f32 v[54:55], v[54:55], v[150:151]
	v_pk_mul_f32 v[64:65], v[64:65], v[160:161]
	v_pk_mul_f32 v[60:61], v[60:61], v[156:157]
	v_pk_mul_f32 v[56:57], v[56:57], v[152:153]
	v_pk_mul_f32 v[52:53], v[52:53], v[148:149]
	v_pk_mul_f32 v[50:51], v[50:51], v[146:147]
	v_pk_mul_f32 v[46:47], v[46:47], v[158:159]
	v_pk_mul_f32 v[42:43], v[42:43], v[154:155]
	v_pk_mul_f32 v[38:39], v[38:39], v[150:151]
	v_pk_mul_f32 v[48:49], v[48:49], v[160:161]
	v_pk_mul_f32 v[44:45], v[44:45], v[156:157]
	v_pk_mul_f32 v[40:41], v[40:41], v[152:153]
	v_pk_mul_f32 v[36:37], v[36:37], v[148:149]
	v_pk_mul_f32 v[34:35], v[34:35], v[146:147]
	v_pk_mul_f32 v[30:31], v[30:31], v[158:159]
	v_pk_mul_f32 v[26:27], v[26:27], v[154:155]
	v_pk_mul_f32 v[22:23], v[22:23], v[150:151]
	v_pk_mul_f32 v[32:33], v[32:33], v[160:161]
	v_pk_mul_f32 v[28:29], v[28:29], v[156:157]
	v_pk_mul_f32 v[24:25], v[24:25], v[152:153]
	v_pk_mul_f32 v[20:21], v[20:21], v[148:149]
	v_pk_mul_f32 v[18:19], v[18:19], v[146:147]
	v_pk_mul_f32 v[14:15], v[14:15], v[158:159]
	v_pk_mul_f32 v[10:11], v[10:11], v[154:155]
	v_pk_mul_f32 v[6:7], v[6:7], v[150:151]
	v_pk_mul_f32 v[16:17], v[16:17], v[160:161]
	v_pk_mul_f32 v[12:13], v[12:13], v[156:157]
	v_pk_mul_f32 v[8:9], v[8:9], v[152:153]
	v_pk_mul_f32 v[4:5], v[4:5], v[148:149]
	v_pk_mul_f32 v[2:3], v[2:3], v[146:147]

; template <bool WIN>
; __device__ __forceinline__ void partialSM(f32x16& p0, f32x16& p1, float& m_reg, float& mn, float& alpha) {
;   constexpr float C = SCALE * 1.4426950408889634f;
;   float pmax = p0[0];
; #pragma unroll
;   for (int r = 1; r < 16; ++r) pmax = fmaxf(pmax, p0[r]);
; #pragma unroll
;   for (int r = 0; r < 16; ++r) pmax = fmaxf(pmax, p1[r]);
;   { auto rr = __builtin_amdgcn_permlane32_swap(__float_as_uint(pmax), __float_as_uint(pmax), false, false);
;     pmax = fmaxf(__uint_as_float(rr[0]), __uint_as_float(rr[1])); }
;   if (__builtin_expect(__all(pmax - m_reg <= THR / SCALE), 1)) { mn = m_reg; alpha = 1.f; }
;   else { mn = fmaxf(m_reg, pmax); alpha = __builtin_amdgcn_exp2f((m_reg - mn) * C); m_reg = mn; }
;   float mnC = -mn * C;
; #pragma unroll
;   for (int r = 0; r < 16; ++r) p0[r] = fmaf(p0[r], C, mnC);
; #pragma unroll
;   for (int r = 0; r < 16; ++r) p1[r] = fmaf(p1[r], C, mnC);
; #pragma unroll
;   for (int r = 0; r < 16; ++r) p0[r] = __builtin_amdgcn_exp2f(p0[r]);
; }
; __device__ __forceinline__ void finishSM(f32x16& p0, f32x16& p1, float alpha, float& l_reg, bf16x8& pa0, bf16x8& pa1, bf16x8& pa2, bf16x8& pa3) {
; #pragma unroll
;   for (int r = 0; r < 16; ++r) p1[r] = __builtin_amdgcn_exp2f(p1[r]);
;   float ps = 0;
; #pragma unroll
;   for (int r = 0; r < 16; ++r) ps += p0[r];
; #pragma unroll
;   for (int r = 0; r < 16; ++r) ps += p1[r];
;   { auto rr = __builtin_amdgcn_permlane32_swap(__float_as_uint(ps), __float_as_uint(ps), false, false);
;     ps = __uint_as_float(rr[0]) + __uint_as_float(rr[1]); }
;   l_reg = l_reg * alpha + ps;
;     ...
;   PK4(p0, 0, pa0); PK4(p0, 8, pa1); PK4(p1, 0, pa2); PK4(p1, 8, pa3);
;     ...
; }
; template <bool WIN>
; __device__ __forceinline__ void qkt(f32x16& p0, f32x16& p1, const bf16_t* Ks, const bf16x8* qr, int r32, int hi, int dq) {
;   p0 = f32x16{}; p1 = f32x16{};
;   if (WIN) {
;     const int t = 4 * hi - dq + 128;
; #pragma unroll
;     for (int r = 0; r < 16; ++r) { const unsigned d0 = (unsigned)(t + (r & 3) + 8 * (r >> 2)), d1 = d0 + 32u;
;       p0[r] = d0 > 256u ? -1e30f : 0.f; p1[r] = d1 > 256u ? -1e30f : 0.f; }
;   }
; #pragma unroll
;   for (int d0 = 0; d0 < 8; ++d0) { int cb = (d0 * 16 + hi * 8) * 2;
;     bf16x8 b0 = *reinterpret_cast<const bf16x8*>((const char*)Ks + KSWZ(r32, cb));
;     bf16x8 b1 = *reinterpret_cast<const bf16x8*>((const char*)Ks + KSWZ(32 + r32, cb));
.Lpl_top:
	s_and_b32 s69, s68, 1
	s_setprio 1
	s_lshl_b32 s0, s69, 14
	v_add3_u32 v0, s0, v209, v199
	ds_read_b128 v[130:133], v0
	ds_read_b128 v[134:137], v0 offset:8192
	v_add3_u32 v0, s0, v210, v199
	ds_read_b128 v[232:235], v0
	ds_read_b128 v[236:239], v0 offset:8192
	v_add3_u32 v0, s0, v211, v199
	ds_read_b128 v[246:249], v0
	ds_read_b128 v[250:253], v0 offset:8192
	s_waitcnt lgkmcnt(4)
	v_mfma_f32_32x32x16_bf16 v[146:161], v[130:133], v[162:165], 0
	v_mfma_f32_32x32x16_bf16 v[130:145], v[134:137], v[162:165], 0
	s_waitcnt lgkmcnt(2)
	v_mfma_f32_32x32x16_bf16 v[146:161], v[232:235], v[166:169], v[146:161]
	v_mfma_f32_32x32x16_bf16 v[130:145], v[236:239], v[166:169], v[130:145]
	v_add3_u32 v0, s0, v212, v199
	ds_read_b128 v[232:235], v0
	ds_read_b128 v[236:239], v0 offset:8192
	s_waitcnt lgkmcnt(2)
	v_mfma_f32_32x32x16_bf16 v[146:161], v[246:249], v[170:173], v[146:161]
	v_mfma_f32_32x32x16_bf16 v[130:145], v[250:253], v[170:173], v[130:145]
	v_add3_u32 v0, s0, v213, v199
	ds_read_b128 v[246:249], v0
	ds_read_b128 v[250:253], v0 offset:8192
	s_waitcnt lgkmcnt(2)
	v_mfma_f32_32x32x16_bf16 v[146:161], v[232:235], v[174:177], v[146:161]
	v_mfma_f32_32x32x16_bf16 v[130:145], v[236:239], v[174:177], v[130:145]
	v_add3_u32 v0, s0, v214, v199
	ds_read_b128 v[232:235], v0
	ds_read_b128 v[236:239], v0 offset:8192
	s_waitcnt lgkmcnt(2)
	v_mfma_f32_32x32x16_bf16 v[146:161], v[246:249], v[178:181], v[146:161]
	v_mfma_f32_32x32x16_bf16 v[130:145], v[250:253], v[178:181], v[130:145]
	v_add3_u32 v0, s0, v215, v199
	ds_read_b128 v[246:249], v0
	ds_read_b128 v[250:253], v0 offset:8192
	s_waitcnt lgkmcnt(2)
	v_mfma_f32_32x32x16_bf16 v[146:161], v[232:235], v[182:185], v[146:161]
	v_mfma_f32_32x32x16_bf16 v[130:145], v[236:239], v[182:185], v[130:145]
	v_add3_u32 v0, s0, v216, v199
	ds_read_b128 v[232:235], v0
	ds_read_b128 v[236:239], v0 offset:8192
	s_waitcnt lgkmcnt(2)
	v_mfma_f32_32x32x16_bf16 v[146:161], v[246:249], v[186:189], v[146:161]
	v_mfma_f32_32x32x16_bf16 v[130:145], v[250:253], v[186:189], v[130:145]
	s_waitcnt lgkmcnt(0)
	v_mfma_f32_32x32x16_bf16 v[146:161], v[232:235], v[190:193], v[146:161]
	v_mfma_f32_32x32x16_bf16 v[130:145], v[236:239], v[190:193], v[130:145]
	s_setprio 0
	s_nop 7
	s_nop 1
	v_max3_f32 v0, v146, v147, v148
	v_max3_f32 v231, v130, v131, v132
	v_max3_f32 v0, v0, v149, v150
	v_max3_f32 v231, v231, v133, v134
	v_max3_f32 v0, v0, v151, v152
	v_max3_f32 v231, v231, v135, v136
	v_max3_f32 v0, v0, v153, v154
	v_max3_f32 v231, v231, v137, v138
	v_max3_f32 v0, v0, v155, v156
	v_max3_f32 v231, v231, v139, v140
	v_max3_f32 v0, v0, v157, v158
	v_max3_f32 v231, v231, v141, v142
	v_max3_f32 v0, v0, v159, v160
	v_max3_f32 v231, v231, v143, v144
	v_max3_f32 v0, v0, v161, v231
	v_max_f32_e32 v0, v0, v145
	v_mov_b32_e32 v231, v0
	s_nop 1
	v_permlane32_swap_b32_e32 v0, v231
	v_max_f32_e32 v0, v0, v231
	v_sub_f32_e32 v231, v0, v229
	s_mov_b32 s0, 0x42b504f3
	v_cmp_ge_f32_e32 vcc, s0, v231
	v_max_f32_e32 v232, v229, v0
	s_cmp_eq_u64 vcc, exec
	s_cselect_b64 vcc, -1, 0
	v_sub_f32_e32 v0, v229, v232
	v_cndmask_b32_e32 v229, v232, v229, vcc
	v_mul_f32_e32 v231, 0xbe0293ee, v229
	v_fmamk_f32 v146, v146, 0x3e0293ee, v231
	v_fmamk_f32 v147, v147, 0x3e0293ee, v231
	v_fmamk_f32 v148, v148, 0x3e0293ee, v231
	v_fmamk_f32 v149, v149, 0x3e0293ee, v231
	v_fmamk_f32 v150, v150, 0x3e0293ee, v231
	v_fmamk_f32 v151, v151, 0x3e0293ee, v231
	v_fmamk_f32 v152, v152, 0x3e0293ee, v231
	v_fmamk_f32 v153, v153, 0x3e0293ee, v231
	v_fmamk_f32 v154, v154, 0x3e0293ee, v231
	v_fmamk_f32 v155, v155, 0x3e0293ee, v231
	v_fmamk_f32 v156, v156, 0x3e0293ee, v231
	v_fmamk_f32 v157, v157, 0x3e0293ee, v231
	v_fmamk_f32 v158, v158, 0x3e0293ee, v231
	v_fmamk_f32 v159, v159, 0x3e0293ee, v231
	v_fmamk_f32 v160, v160, 0x3e0293ee, v231
	v_fmamk_f32 v161, v161, 0x3e0293ee, v231
	v_fmamk_f32 v130, v130, 0x3e0293ee, v231
	v_fmamk_f32 v131, v131, 0x3e0293ee, v231
	v_fmamk_f32 v132, v132, 0x3e0293ee, v231
	v_fmamk_f32 v133, v133, 0x3e0293ee, v231
	v_fmamk_f32 v134, v134, 0x3e0293ee, v231
	v_fmamk_f32 v135, v135, 0x3e0293ee, v231
	v_fmamk_f32 v136, v136, 0x3e0293ee, v231
	v_fmamk_f32 v137, v137, 0x3e0293ee, v231
	v_fmamk_f32 v138, v138, 0x3e0293ee, v231
	v_fmamk_f32 v139, v139, 0x3e0293ee, v231
	v_fmamk_f32 v140, v140, 0x3e0293ee, v231
	v_fmamk_f32 v141, v141, 0x3e0293ee, v231
	v_fmamk_f32 v142, v142, 0x3e0293ee, v231
	v_fmamk_f32 v143, v143, 0x3e0293ee, v231
	v_fmamk_f32 v144, v144, 0x3e0293ee, v231
	v_fmac_f32_e32 v231, 0x3e0293ee, v145
	v_exp_f32_e32 v145, v146
	v_exp_f32_e32 v146, v147
	v_exp_f32_e32 v147, v148
	v_exp_f32_e32 v148, v149
	v_exp_f32_e32 v149, v150
	v_exp_f32_e32 v150, v151
	v_exp_f32_e32 v151, v152
	v_exp_f32_e32 v152, v153
	v_exp_f32_e32 v153, v154
	v_exp_f32_e32 v154, v155
	v_exp_f32_e32 v155, v156
	v_exp_f32_e32 v156, v157
	v_exp_f32_e32 v157, v158
	v_exp_f32_e32 v158, v159
	v_exp_f32_e32 v159, v160
	v_exp_f32_e32 v160, v161
	v_exp_f32_e32 v161, v134
	v_add_f32_e32 v134, v146, v145
	v_add_f32_e32 v134, v147, v134
	v_add_f32_e32 v134, v148, v134
	v_add_f32_e32 v134, v149, v134
	v_add_f32_e32 v134, v150, v134
	v_add_f32_e32 v134, v151, v134
	v_add_f32_e32 v134, v152, v134
	v_add_f32_e32 v134, v153, v134
	v_add_f32_e32 v134, v154, v134
	v_add_f32_e32 v134, v155, v134
	v_add_f32_e32 v134, v156, v134
	v_exp_f32_e32 v130, v130
	v_add_f32_e32 v134, v157, v134
; __device__ __forceinline__ void finishSM(f32x16& p0, f32x16& p1, float alpha, float& l_reg, bf16x8& pa0, bf16x8& pa1, bf16x8& pa2, bf16x8& pa3) {
; #pragma unroll
;   for (int r = 0; r < 16; ++r) p1[r] = __builtin_amdgcn_exp2f(p1[r]);
;   float ps = 0;
; #pragma unroll
;   for (int r = 0; r < 16; ++r) ps += p0[r];
; #pragma unroll
;   for (int r = 0; r < 16; ++r) ps += p1[r];
;   { auto rr = __builtin_amdgcn_permlane32_swap(__float_as_uint(ps), __float_as_uint(ps), false, false);
;     ps = __uint_as_float(rr[0]) + __uint_as_float(rr[1]); }
;   l_reg = l_reg * alpha + ps;
;     ...
;   PK4(p0, 0, pa0); PK4(p0, 8, pa1); PK4(p1, 0, pa2); PK4(p1, 8, pa3);
;     ...
; }
	v_exp_f32_e32 v131, v131
	v_add_f32_e32 v134, v158, v134
	v_exp_f32_e32 v132, v132
	v_add_f32_e32 v134, v159, v134
	v_exp_f32_e32 v133, v133
	v_add_f32_e32 v134, v160, v134
	v_add_f32_e32 v134, v130, v134
	v_exp_f32_e32 v233, v135
	v_add_f32_e32 v134, v131, v134
	v_exp_f32_e32 v234, v136
	v_add_f32_e32 v134, v132, v134
	v_exp_f32_e32 v235, v137
	v_add_f32_e32 v134, v133, v134
	v_exp_f32_e32 v138, v138
	v_add_f32_e32 v134, v161, v134
	v_exp_f32_e32 v139, v139
	v_add_f32_e32 v134, v233, v134
	v_exp_f32_e32 v140, v140
	v_add_f32_e32 v134, v234, v134
	v_exp_f32_e32 v141, v141
	v_add_f32_e32 v134, v235, v134
	v_exp_f32_e32 v236, v142
	v_add_f32_e32 v134, v138, v134
	v_exp_f32_e32 v237, v143
	v_add_f32_e32 v134, v139, v134
	v_exp_f32_e32 v238, v144
	v_add_f32_e32 v134, v140, v134
	v_mul_f32_e32 v0, 0x3e0293ee, v0
	v_exp_f32_e32 v239, v231
	v_add_f32_e32 v134, v141, v134
	v_exp_f32_e32 v0, v0
	v_add_f32_e32 v134, v236, v134
	v_add_f32_e32 v134, v237, v134
	v_add_f32_e32 v134, v238, v134
	v_add_f32_e32 v231, v239, v134
	v_cndmask_b32_e64 v0, v0, 1.0, vcc
	v_mov_b32_e32 v232, v231
	v_cvt_pk_bf16_f32 v134, v145, v146
	v_cvt_pk_bf16_f32 v135, v147, v148
	v_cvt_pk_bf16_f32 v136, v149, v150
	v_cvt_pk_bf16_f32 v137, v151, v152
	v_cvt_pk_bf16_f32 v142, v153, v154
	v_cvt_pk_bf16_f32 v143, v155, v156
	v_cvt_pk_bf16_f32 v144, v157, v158
	v_cvt_pk_bf16_f32 v145, v159, v160
	v_cvt_pk_bf16_f32 v130, v130, v131
	v_cvt_pk_bf16_f32 v131, v132, v133
	v_cvt_pk_bf16_f32 v132, v161, v233
	v_cvt_pk_bf16_f32 v133, v234, v235
	v_cvt_pk_bf16_f32 v138, v138, v139
	v_cvt_pk_bf16_f32 v139, v140, v141
	v_cvt_pk_bf16_f32 v140, v236, v237
	v_cvt_pk_bf16_f32 v141, v238, v239
	v_permlane32_swap_b32_e32 v231, v232
	v_permlane32_swap_b32_e32 v134, v136
	v_permlane32_swap_b32_e32 v135, v137
	v_permlane32_swap_b32_e32 v142, v144
	v_permlane32_swap_b32_e32 v143, v145
	v_permlane32_swap_b32_e32 v130, v132
	v_permlane32_swap_b32_e32 v131, v133
	v_permlane32_swap_b32_e32 v138, v140
	v_permlane32_swap_b32_e32 v139, v141
	v_cmp_gt_f32_e32 vcc, 1.0, v0
	s_cbranch_vccz .Lpl_649
	s_and_saveexec_b64 s[0:1], s[6:7]
	ds_write_b32 v228, v0 offset:128
	s_or_b64 exec, exec, s[0:1]
	s_waitcnt lgkmcnt(0)
	v_add_u32_e32 v146, s67, v223
	ds_read_b128 v[158:161], v146 offset:224
	ds_read_b128 v[154:157], v146 offset:192
	ds_read_b128 v[150:153], v146 offset:160
	ds_read_b128 v[146:149], v146 offset:128
	s_waitcnt lgkmcnt(0)
	v_pk_mul_f32 v[126:127], v[126:127], v[158:159]
	v_pk_mul_f32 v[122:123], v[122:123], v[154:155]
	v_pk_mul_f32 v[118:119], v[118:119], v[150:151]
	v_pk_mul_f32 v[128:129], v[128:129], v[160:161]
	v_pk_mul_f32 v[124:125], v[124:125], v[156:157]
	v_pk_mul_f32 v[120:121], v[120:121], v[152:153]
	v_pk_mul_f32 v[116:117], v[116:117], v[148:149]
	v_pk_mul_f32 v[114:115], v[114:115], v[146:147]
	v_pk_mul_f32 v[110:111], v[110:111], v[158:159]
	v_pk_mul_f32 v[106:107], v[106:107], v[154:155]
	v_pk_mul_f32 v[102:103], v[102:103], v[150:151]
	v_pk_mul_f32 v[112:113], v[112:113], v[160:161]
	v_pk_mul_f32 v[108:109], v[108:109], v[156:157]
	v_pk_mul_f32 v[104:105], v[104:105], v[152:153]
	v_pk_mul_f32 v[100:101], v[100:101], v[148:149]
	v_pk_mul_f32 v[98:99], v[98:99], v[146:147]
	v_pk_mul_f32 v[94:95], v[94:95], v[158:159]
	v_pk_mul_f32 v[90:91], v[90:91], v[154:155]
	v_pk_mul_f32 v[86:87], v[86:87], v[150:151]
	v_pk_mul_f32 v[96:97], v[96:97], v[160:161]
	v_pk_mul_f32 v[92:93], v[92:93], v[156:157]
	v_pk_mul_f32 v[88:89], v[88:89], v[152:153]
	v_pk_mul_f32 v[84:85], v[84:85], v[148:149]
	v_pk_mul_f32 v[82:83], v[82:83], v[146:147]
	v_pk_mul_f32 v[78:79], v[78:79], v[158:159]
	v_pk_mul_f32 v[74:75], v[74:75], v[154:155]
	v_pk_mul_f32 v[70:71], v[70:71], v[150:151]
	v_pk_mul_f32 v[80:81], v[80:81], v[160:161]
	v_pk_mul_f32 v[76:77], v[76:77], v[156:157]
	v_pk_mul_f32 v[72:73], v[72:73], v[152:153]
	v_pk_mul_f32 v[68:69], v[68:69], v[148:149]
	v_pk_mul_f32 v[66:67], v[66:67], v[146:147]
	v_pk_mul_f32 v[62:63], v[62:63], v[158:159]
	v_pk_mul_f32 v[58:59], v[58:59], v[154:155]
	v_pk_mul_f32 v[54:55], v[54:55], v[150:151]
	v_pk_mul_f32 v[64:65], v[64:65], v[160:161]
	v_pk_mul_f32 v[60:61], v[60:61], v[156:157]
	v_pk_mul_f32 v[56:57], v[56:57], v[152:153]
	v_pk_mul_f32 v[52:53], v[52:53], v[148:149]
	v_pk_mul_f32 v[50:51], v[50:51], v[146:147]
	v_pk_mul_f32 v[46:47], v[46:47], v[158:159]
	v_pk_mul_f32 v[42:43], v[42:43], v[154:155]
	v_pk_mul_f32 v[38:39], v[38:39], v[150:151]
	v_pk_mul_f32 v[48:49], v[48:49], v[160:161]
	v_pk_mul_f32 v[44:45], v[44:45], v[156:157]
	v_pk_mul_f32 v[40:41], v[40:41], v[152:153]
	v_pk_mul_f32 v[36:37], v[36:37], v[148:149]
	v_pk_mul_f32 v[34:35], v[34:35], v[146:147]
	v_pk_mul_f32 v[30:31], v[30:31], v[158:159]
	v_pk_mul_f32 v[26:27], v[26:27], v[154:155]
	v_pk_mul_f32 v[22:23], v[22:23], v[150:151]
	v_pk_mul_f32 v[32:33], v[32:33], v[160:161]
	v_pk_mul_f32 v[28:29], v[28:29], v[156:157]
	v_pk_mul_f32 v[24:25], v[24:25], v[152:153]
	v_pk_mul_f32 v[20:21], v[20:21], v[148:149]
	v_pk_mul_f32 v[18:19], v[18:19], v[146:147]
	v_pk_mul_f32 v[14:15], v[14:15], v[158:159]
	v_pk_mul_f32 v[10:11], v[10:11], v[154:155]
	v_pk_mul_f32 v[6:7], v[6:7], v[150:151]
	v_pk_mul_f32 v[16:17], v[16:17], v[160:161]
	v_pk_mul_f32 v[12:13], v[12:13], v[156:157]
	v_pk_mul_f32 v[8:9], v[8:9], v[152:153]
	v_pk_mul_f32 v[4:5], v[4:5], v[148:149]
	v_pk_mul_f32 v[2:3], v[2:3], v[146:147]
